# speedup vs baseline: 1.0077x; 1.0077x over previous
; DI int my_tid() { int t = tid_raw(); asm volatile("" : "+v"(t)); return t; }
; DI int crow(int reg, int h) { return (reg & 3) + 8 * (reg >> 2) + 4 * h; }
; DI void attn_task(const Params& p, int hd, int qb) {
;   const int lane = my_tid() & 63, r = lane & 31, hh = lane >> 5;
;   const u16* QK = (const u16*)(p.ws + OFF_QK);
;   const u16* VT = (const u16*)(p.ws + OFF_VT) + ((size_t)(hd * 512) * 64 + r) * 32 + 8 * hh;
;   bf16x8 qf[4];
; #pragma unroll
;   for (int ks = 0; ks < 4; ++ks) qf[ks] = *(const bf16x8*)(QK + (size_t)(32 * qb + r) * 512 + hd * 64 + 16 * ks + 8 * hh);
;   bf16x8 tri[2];
; #pragma unroll
;   for (int s2 = 0; s2 < 2; ++s2)
; #pragma unroll
;     for (int jj = 0; jj < 8; ++jj) tri[s2][jj] = (crow(8 * s2 + jj, hh) >= r) ? (short)0x3F80 : (short)0;
;   f32x16 o0, o1;
; #pragma unroll
;   for (int e = 0; e < 16; ++e) { o0[e] = 0.f; o1[e] = 0.f; }
;   float carry = 0.f;
;   const u16* Kbase = (const u16*)(p.ws + OFF_QK + 16 * MiB) + (size_t)(hd * 512) * 2048 + r * 16 + 8 * hh;
;   bf16x8 kf[4];
; #pragma unroll
;   for (int ks = 0; ks < 4; ++ks) kf[ks] = *(const bf16x8*)(Kbase + (size_t)qb * 2048 + ks * 512);
; __global__ void __launch_bounds__(512, 2) fwd_megakernel(Params p) {
;     ...
;       for (int g2 = blockIdx.x; g2 < 256; g2 += gridDim.x)
; #pragma unroll 1
;         for (int rr = 0; rr < 2; ++rr) attn_task(p, g2 & 7, 511 - ((g2 >> 3) * 16 + rr * 8 + (my_tid() >> 6)));
.LBB0_788:
	s_getreg_b32 s8, hwreg(HW_REG_HW_ID, 0, 6)
	s_lshl_b32 s8, s8, 2
	s_and_b32 s8, s8, 0xfc
	s_add_i32 s8, s8, 0x20040
	v_mov_b32_e32 v0, s8
	ds_read_b32 v0, v0
	s_or_b32 s8, s97, s96
	v_mov_b32_e32 v16, 0
	v_mov_b32_e32 v17, 0
	v_mov_b32_e32 v18, 0
	s_waitcnt lgkmcnt(0)
	v_readfirstlane_b32 s9, v0
	v_mov_b32_e32 v19, 0
	v_mov_b32_e32 v20, 0
	v_lshl_or_b32 v0, s9, 6, v214
	s_getreg_b32 s9, hwreg(HW_REG_HW_ID, 0, 6)
	s_lshl_b32 s9, s9, 2
	s_and_b32 s9, s9, 0xfc
	s_add_i32 s9, s9, 0x20040
	v_mov_b32_e32 v1, s9
	ds_read_b32 v1, v1
	v_ashrrev_i32_e32 v46, 6, v0
	v_add_u32_e32 v48, s8, v46
	s_movk_i32 s8, 0x200
	v_cmp_gt_i32_e32 vcc, s8, v48
	s_waitcnt lgkmcnt(0)
	v_readfirstlane_b32 s8, v1
	v_sub_u32_e32 v108, 0x1ff, v48
	v_mov_b32_e32 v21, 0
	v_lshl_or_b32 v47, s8, 6, v214
	v_mov_b32_e32 v22, 0
	v_and_b32_e32 v32, 31, v47
	v_bfe_u32 v33, v47, 5, 1
	v_lshl_or_b32 v106, v108, 5, v32
	v_lshlrev_b32_e32 v114, 2, v33
	v_ashrrev_i32_e32 v107, 31, v106
	v_mov_b32_e32 v23, 0
	v_mov_b32_e32 v24, 0
	v_mov_b32_e32 v25, 0
	v_mov_b32_e32 v26, 0
	v_mov_b32_e32 v27, 0
	v_mov_b32_e32 v28, 0
	v_mov_b32_e32 v29, 0
	v_mov_b32_e32 v30, 0
	v_mov_b32_e32 v31, 0
	v_mov_b32_e32 v0, 0
	v_mov_b32_e32 v1, 0
	v_mov_b32_e32 v2, 0
	v_mov_b32_e32 v3, 0
	v_mov_b32_e32 v4, 0
	v_mov_b32_e32 v5, 0
	v_mov_b32_e32 v6, 0
	v_mov_b32_e32 v7, 0
	v_mov_b32_e32 v8, 0
	v_mov_b32_e32 v9, 0
	v_mov_b32_e32 v10, 0
	v_mov_b32_e32 v11, 0
	v_mov_b32_e32 v12, 0
	v_mov_b32_e32 v13, 0
	v_mov_b32_e32 v14, 0
	v_mov_b32_e32 v15, 0
	s_and_saveexec_b64 s[8:9], vcc
	s_cbranch_execz .LBB0_787
	v_or_b32_e32 v6, 27, v114
	v_cmp_lt_u32_e32 vcc, v6, v32
	v_or_b32_e32 v6, 26, v114
	v_cmp_lt_u32_e64 s[38:39], v6, v32
	v_or_b32_e32 v6, 25, v114
	v_cmp_lt_u32_e64 s[40:41], v6, v32
	v_or_b32_e32 v6, 24, v114
	v_cmp_lt_u32_e64 s[42:43], v6, v32
	v_or_b32_e32 v6, 19, v114
	v_cmp_lt_u32_e64 s[44:45], v6, v32
	v_or_b32_e32 v6, 18, v114
	v_cmp_lt_u32_e64 s[46:47], v6, v32
	v_or_b32_e32 v6, 17, v114
	v_cmp_lt_u32_e64 s[48:49], v6, v32
	v_or_b32_e32 v6, 16, v114
	v_cmp_lt_u32_e64 s[50:51], v6, v32
	v_or_b32_e32 v6, 11, v114
	v_cmp_lt_u32_e64 s[52:53], v6, v32
	v_or_b32_e32 v6, 10, v114
	v_cmp_lt_u32_e64 s[54:55], v6, v32
	v_or_b32_e32 v6, 9, v114
	v_lshlrev_b32_e32 v64, 5, v32
	v_cmp_lt_u32_e64 s[56:57], v6, v32
	v_or_b32_e32 v6, 8, v114
	v_lshlrev_b32_e32 v44, 6, v32
	v_mov_b32_e32 v45, v65
	v_lshl_add_u64 v[4:5], s[22:23], 0, v[64:65]
	v_lshlrev_b32_e32 v2, 4, v33
	v_mov_b32_e32 v3, v65
	v_cmp_lt_u32_e64 s[58:59], v6, v32
	v_or_b32_e32 v6, 3, v114
	v_mov_b32_e32 v109, v65
	v_lshlrev_b64 v[10:11], 10, v[106:107]
	v_lshl_add_u64 v[0:1], s[36:37], 0, v[44:45]
	v_lshl_add_u64 v[4:5], v[4:5], 0, v[2:3]
	v_cmp_lt_u32_e64 s[60:61], v6, v32
	v_or_b32_e32 v6, 2, v114
	v_lshlrev_b64 v[8:9], 12, v[108:109]
	v_lshl_add_u64 v[10:11], s[94:95], 0, v[10:11]
	v_lshl_add_u64 v[0:1], v[0:1], 0, v[2:3]
	v_cmp_lt_u32_e64 s[62:63], v6, v32
	v_or_b32_e32 v6, 1, v114
	v_lshl_add_u64 v[4:5], v[4:5], 0, v[8:9]
	v_lshl_add_u64 v[2:3], v[10:11], 0, v[2:3]
	v_cmp_lt_u32_e64 s[64:65], v6, v32
	global_load_dwordx4 v[24:27], v[4:5], off offset:3072
	global_load_dwordx4 v[28:31], v[4:5], off offset:2048
	global_load_dwordx4 v[40:43], v[4:5], off offset:1024
	s_nop 0
	global_load_dwordx4 v[4:7], v[4:5], off
	s_nop 0
	global_load_dwordx4 v[66:69], v[2:3], off offset:96
	global_load_dwordx4 v[70:73], v[2:3], off offset:64
	global_load_dwordx4 v[74:77], v[2:3], off offset:32
	global_load_dwordx4 v[78:81], v[2:3], off
	v_and_b32_e32 v12, 63, v47
	v_lshlrev_b32_e32 v2, 2, v12
	v_lshl_add_u64 v[0:1], v[0:1], 0, v[8:9]
	v_cmp_lt_u32_e64 s[66:67], v114, v32
	v_xor_b32_e32 v109, 0x80, v2
	global_load_dwordx4 v[20:23], v[0:1], off
	global_load_dwordx4 v[16:19], v[0:1], off offset:2048
	global_load_dwordx4 v[36:39], v[0:1], off offset:32
	global_load_dwordx4 v[32:35], v[0:1], off offset:2080
	v_cndmask_b32_e64 v56, v220, 0, s[52:53]
	v_cndmask_b32_e64 v57, v220, 0, s[54:55]
	v_cndmask_b32_e64 v58, v220, 0, s[56:57]
	v_cndmask_b32_e64 v59, v220, 0, s[58:59]
	v_cndmask_b32_e64 v60, v220, 0, s[60:61]
	v_cndmask_b32_e64 v61, v220, 0, s[62:63]
	v_cndmask_b32_e64 v62, v220, 0, s[64:65]
	v_cndmask_b32_e64 v63, v220, 0, s[66:67]
	v_perm_b32 v85, v56, v57, s33
	v_perm_b32 v84, v58, v59, s33
	v_perm_b32 v83, v60, v61, s33
	v_cndmask_b32_e64 v45, v220, 0, vcc
	v_cndmask_b32_e64 v49, v220, 0, s[38:39]
	v_cndmask_b32_e64 v50, v220, 0, s[40:41]
	v_cndmask_b32_e64 v51, v220, 0, s[42:43]
	v_cndmask_b32_e64 v52, v220, 0, s[44:45]
	v_cndmask_b32_e64 v53, v220, 0, s[46:47]
	v_cndmask_b32_e64 v54, v220, 0, s[48:49]
	v_cndmask_b32_e64 v55, v220, 0, s[50:51]
	s_waitcnt vmcnt(4)
; DI unsigned pk_bf16(float lo, float hi) { f32x2_t v = {lo, hi}; return __builtin_bit_cast(unsigned, __builtin_convertvector(v, bf16x2_t)); }
; DI float bflo(unsigned u) { return __uint_as_float(u << 16); }
; DI float bfhi(unsigned u) { return __uint_as_float(u & 0xffff0000u); }
; DI float shfl_xor_l(float v, int mask, int lane) { return __int_as_float(__builtin_amdgcn_ds_bpermute((lane ^ mask) << 2, __float_as_int(v))); }
; DI int crow(int reg, int h) { return (reg & 3) + 8 * (reg >> 2) + 4 * h; }
; #define MFMA32(a, b, c) __builtin_amdgcn_mfma_f32_32x32x16_bf16((a), (b), (c), 0, 0, 0)
; DI void attn_task(const Params& p, int hd, int qb) {
;     ...
;     f32x16 z;
; #pragma unroll
;     for (int e = 0; e < 16; ++e) z[e] = 0.f;
; #pragma unroll
;     for (int ks = 0; ks < 4; ++ks) z = MFMA32(kf[ks], qf[ks], z);
;     const bool diag = (kb == qb);
;     f32x16 lf;
;     float sum = 0.f;
; #pragma unroll
;     for (int e = 0; e < 16; ++e) {
;       const float zz = z[e];
;       float l = -__builtin_amdgcn_logf(1.0f + __builtin_amdgcn_exp2f(zz));
;       l = (zz > 30.f) ? -zz : l;
;       if (diag && crow(e, hh) >= r) l = 0.f;
;       lf[e] = l; sum += l;
;     }
;     sum += shfl_xor_l(sum, 32, lane);
;     f32x16 ee = z;
; #pragma unroll
;     for (int s2 = 0; s2 < 2; ++s2) {
;       u32x4 hi, lo;
; #pragma unroll
;       for (int j = 0; j < 4; ++j) {
;         const float a = lf[8 * s2 + 2 * j], b = lf[8 * s2 + 2 * j + 1];
;         hi[j] = pk_bf16(a, b);
;         lo[j] = pk_bf16(a - bflo(hi[j]), b - bfhi(hi[j]));
;       }
;       ee = MFMA32(tri[s2], __builtin_bit_cast(bf16x8, hi), ee);
;       ee = MFMA32(tri[s2], __builtin_bit_cast(bf16x8, lo), ee);
;     }
	v_mfma_f32_32x32x16_bf16 v[0:15], v[4:7], v[78:81], 0
	v_mfma_f32_32x32x16_bf16 v[0:15], v[40:43], v[74:77], v[0:15]
	v_mfma_f32_32x32x16_bf16 v[0:15], v[28:31], v[70:73], v[0:15]
	v_mfma_f32_32x32x16_bf16 v[0:15], v[24:27], v[66:69], v[0:15]
	s_nop 11
	v_exp_f32_e32 v24, v0
	v_exp_f32_e32 v25, v1
	v_cmp_lt_f32_e64 s[68:69], s79, v0
	v_exp_f32_e32 v41, v8
	v_add_f32_e32 v24, 1.0, v24
	v_log_f32_e32 v24, v24
	v_add_f32_e32 v25, 1.0, v25
	v_log_f32_e32 v25, v25
	v_add_f32_e32 v41, 1.0, v41
	v_cndmask_b32_e64 v24, v24, v0, s[68:69]
	v_cmp_lt_f32_e64 s[68:69], s79, v1
	v_cndmask_b32_e64 v24, 0, -v24, s[66:67]
	v_add_f32_e32 v26, 0, v24
	v_cndmask_b32_e64 v25, v25, v1, s[68:69]
	v_cndmask_b32_e64 v25, 0, -v25, s[64:65]
	v_add_f32_e32 v27, v25, v26
	v_exp_f32_e32 v26, v2
	v_cmp_lt_f32_e64 s[68:69], s79, v2
	v_log_f32_e32 v41, v41
	v_cvt_pk_bf16_f32 v86, v24, v25
	v_add_f32_e32 v26, 1.0, v26
	v_log_f32_e32 v26, v26
	v_lshlrev_b32_e32 v82, 16, v86
	v_sub_f32_e32 v24, v24, v82
	v_and_b32_e32 v82, 0xffff0000, v86
	v_cndmask_b32_e64 v26, v26, v2, s[68:69]
	v_cndmask_b32_e64 v26, 0, -v26, s[62:63]
	v_add_f32_e32 v28, v26, v27
	v_exp_f32_e32 v27, v3
	v_cmp_lt_f32_e64 s[68:69], s79, v3
	v_sub_f32_e32 v25, v25, v82
	v_perm_b32 v82, v62, v63, s33
	v_add_f32_e32 v27, 1.0, v27
	v_log_f32_e32 v27, v27
	v_cvt_pk_bf16_f32 v24, v24, v25
	v_cndmask_b32_e64 v27, v27, v3, s[68:69]
	v_cndmask_b32_e64 v27, 0, -v27, s[60:61]
	v_add_f32_e32 v29, v27, v28
	v_exp_f32_e32 v28, v4
	v_cmp_lt_f32_e64 s[68:69], s79, v4
	v_cvt_pk_bf16_f32 v87, v26, v27
	v_lshlrev_b32_e32 v25, 16, v87
	v_add_f32_e32 v28, 1.0, v28
	v_log_f32_e32 v28, v28
	v_sub_f32_e32 v25, v26, v25
	v_and_b32_e32 v26, 0xffff0000, v87
	v_sub_f32_e32 v26, v27, v26
	v_cndmask_b32_e64 v28, v28, v4, s[68:69]
	v_cndmask_b32_e64 v28, 0, -v28, s[58:59]
	v_add_f32_e32 v30, v28, v29
	v_exp_f32_e32 v29, v5
	v_cmp_lt_f32_e64 s[68:69], s79, v5
	v_cvt_pk_bf16_f32 v25, v25, v26
	v_add_f32_e32 v29, 1.0, v29
	v_log_f32_e32 v29, v29
	s_nop 0
	v_cndmask_b32_e64 v29, v29, v5, s[68:69]
	v_cndmask_b32_e64 v29, 0, -v29, s[56:57]
	v_add_f32_e32 v31, v29, v30
	v_exp_f32_e32 v30, v6
	v_cmp_lt_f32_e64 s[68:69], s79, v6
	v_cvt_pk_bf16_f32 v88, v28, v29
	v_lshlrev_b32_e32 v26, 16, v88
	v_add_f32_e32 v30, 1.0, v30
	v_log_f32_e32 v30, v30
	v_and_b32_e32 v27, 0xffff0000, v88
	v_sub_f32_e32 v26, v28, v26
	v_sub_f32_e32 v27, v29, v27
	v_cndmask_b32_e64 v30, v30, v6, s[68:69]
	v_cndmask_b32_e64 v30, 0, -v30, s[54:55]
	v_add_f32_e32 v40, v30, v31
	v_exp_f32_e32 v31, v7
	v_cmp_lt_f32_e64 s[68:69], s79, v7
	v_cvt_pk_bf16_f32 v26, v26, v27
	v_add_f32_e32 v31, 1.0, v31
	v_log_f32_e32 v31, v31
	s_nop 0
	v_cndmask_b32_e64 v31, v31, v7, s[68:69]
	v_cmp_lt_f32_e64 s[68:69], s79, v8
	v_cndmask_b32_e64 v31, 0, -v31, s[52:53]
	v_cvt_pk_bf16_f32 v89, v30, v31
	v_cndmask_b32_e64 v41, v41, v8, s[68:69]
	v_cndmask_b32_e64 v42, 0, -v41, s[50:51]
	v_exp_f32_e32 v41, v9
	v_cmp_lt_f32_e64 s[68:69], s79, v9
	v_lshlrev_b32_e32 v27, 16, v89
	v_and_b32_e32 v28, 0xffff0000, v89
	v_add_f32_e32 v41, 1.0, v41
	v_log_f32_e32 v41, v41
	v_sub_f32_e32 v27, v30, v27
	v_sub_f32_e32 v28, v31, v28
	v_cvt_pk_bf16_f32 v27, v27, v28
	v_cndmask_b32_e64 v41, v41, v9, s[68:69]
	v_cndmask_b32_e64 v43, 0, -v41, s[48:49]
	v_exp_f32_e32 v41, v10
	v_cmp_lt_f32_e64 s[68:69], s79, v10
	v_add_f32_e32 v40, v31, v40
	v_add_f32_e32 v40, v42, v40
	v_add_f32_e32 v41, 1.0, v41
	v_log_f32_e32 v41, v41
	v_add_f32_e32 v40, v43, v40
	v_cndmask_b32_e64 v41, v41, v10, s[68:69]
	v_cndmask_b32_e64 v90, 0, -v41, s[46:47]
	v_exp_f32_e32 v41, v11
	v_cmp_lt_f32_e64 s[68:69], s79, v11
	v_add_f32_e32 v40, v90, v40
	v_add_f32_e32 v41, 1.0, v41
	v_log_f32_e32 v41, v41
	s_nop 0
	v_cndmask_b32_e64 v41, v41, v11, s[68:69]
	v_cndmask_b32_e64 v91, 0, -v41, s[44:45]
	v_exp_f32_e32 v41, v12
	v_cmp_lt_f32_e64 s[68:69], s79, v12
	v_add_f32_e32 v40, v91, v40
	v_add_f32_e32 v41, 1.0, v41
	v_log_f32_e32 v41, v41
	s_nop 0
	v_cndmask_b32_e64 v41, v41, v12, s[68:69]
	v_cndmask_b32_e64 v92, 0, -v41, s[42:43]
	v_exp_f32_e32 v41, v13
	v_cmp_lt_f32_e64 s[68:69], s79, v13
	v_add_f32_e32 v40, v92, v40
	v_add_f32_e32 v41, 1.0, v41
	v_log_f32_e32 v41, v41
	s_nop 0
	v_cndmask_b32_e64 v41, v41, v13, s[68:69]
	v_cndmask_b32_e64 v93, 0, -v41, s[40:41]
	v_exp_f32_e32 v41, v14
	v_cmp_lt_f32_e64 s[68:69], s79, v14
	v_add_f32_e32 v40, v93, v40
	v_add_f32_e32 v41, 1.0, v41
	v_log_f32_e32 v41, v41
	s_nop 0
	v_cndmask_b32_e64 v41, v41, v14, s[68:69]
	v_cndmask_b32_e64 v94, 0, -v41, s[38:39]
	v_exp_f32_e32 v41, v15
	v_cmp_lt_f32_e64 s[68:69], s79, v15
	v_add_f32_e32 v40, v94, v40
	v_add_f32_e32 v41, 1.0, v41
	v_log_f32_e32 v41, v41
	s_nop 0
	v_cndmask_b32_e64 v41, v41, v15, s[68:69]
	v_mfma_f32_32x32x16_bf16 v[0:15], v[82:85], v[86:89], v[0:15]
	v_perm_b32 v89, v45, v49, s33
	v_perm_b32 v88, v50, v51, s33
	v_perm_b32 v87, v52, v53, s33
	v_perm_b32 v86, v54, v55, s33
	v_cndmask_b32_e64 v95, 0, -v41, vcc
	v_add_f32_e32 v40, v95, v40
	ds_bpermute_b32 v41, v109, v40
	v_mfma_f32_32x32x16_bf16 v[0:15], v[82:85], v[24:27], v[0:15]
	v_cvt_pk_bf16_f32 v24, v42, v43
	v_lshlrev_b32_e32 v25, 16, v24
	v_and_b32_e32 v26, 0xffff0000, v24
	v_sub_f32_e32 v25, v42, v25
	v_sub_f32_e32 v26, v43, v26
	v_cvt_pk_bf16_f32 v28, v25, v26
	v_cvt_pk_bf16_f32 v25, v90, v91
	v_lshlrev_b32_e32 v26, 16, v25
	v_and_b32_e32 v27, 0xffff0000, v25
	v_sub_f32_e32 v26, v90, v26
	v_sub_f32_e32 v27, v91, v27
	v_cvt_pk_bf16_f32 v29, v26, v27
	v_cvt_pk_bf16_f32 v26, v92, v93
	v_lshlrev_b32_e32 v27, 16, v26
	v_and_b32_e32 v30, 0xffff0000, v26
	v_sub_f32_e32 v27, v92, v27
	v_sub_f32_e32 v30, v93, v30
	v_cvt_pk_bf16_f32 v30, v27, v30
	v_cvt_pk_bf16_f32 v27, v94, v95
	v_lshlrev_b32_e32 v31, 16, v27
; DI int crow(int reg, int h) { return (reg & 3) + 8 * (reg >> 2) + 4 * h; }
; #define MFMA32(a, b, c) __builtin_amdgcn_mfma_f32_32x32x16_bf16((a), (b), (c), 0, 0, 0)
; DI void attn_task(const Params& p, int hd, int qb) {
;     ...
;     f32x16 wv;
; #pragma unroll
;     for (int e = 0; e < 16; ++e) {
;       float x = __builtin_amdgcn_exp2f(ee[e] + carry);
;       if (diag && crow(e, hh) >= r) x = 0.f;
;       wv[e] = x;
;     }
; #pragma unroll
;     for (int s2 = 0; s2 < 2; ++s2) {
;       const bf16x8 wp = pack8(wv, s2);
;       o0 = MFMA32(vf[s2][0], wp, o0);
;       o1 = MFMA32(vf[s2][1], wp, o1);
;     }
;     carry += sum;
;     if (__all(carry < -160.f)) break;
; #pragma unroll
;     for (int ks = 0; ks < 4; ++ks) kf[ks] = kn[ks];
;   }
	v_and_b32_e32 v42, 0xffff0000, v27
	v_mfma_f32_32x32x16_bf16 v[0:15], v[86:89], v[24:27], v[0:15]
	v_sub_f32_e32 v31, v94, v31
	v_sub_f32_e32 v42, v95, v42
	v_cvt_pk_bf16_f32 v31, v31, v42
	s_nop 1
	v_mfma_f32_32x32x16_bf16 v[0:15], v[86:89], v[28:31], v[0:15]
	s_nop 11
	v_add_f32_e32 v8, 0, v8
	v_exp_f32_e32 v8, v8
	v_add_f32_e32 v0, 0, v0
	v_add_f32_e32 v1, 0, v1
	v_add_f32_e32 v2, 0, v2
	v_cndmask_b32_e64 v42, 0, v8, s[50:51]
	v_add_f32_e32 v8, 0, v9
	v_exp_f32_e32 v8, v8
	v_add_f32_e32 v3, 0, v3
	v_add_f32_e32 v4, 0, v4
	v_add_f32_e32 v5, 0, v5
	v_cndmask_b32_e64 v43, 0, v8, s[48:49]
	v_add_f32_e32 v8, 0, v10
	v_exp_f32_e32 v8, v8
	v_add_f32_e32 v6, 0, v6
	v_add_f32_e32 v7, 0, v7
	v_exp_f32_e32 v0, v0
	v_cndmask_b32_e64 v45, 0, v8, s[46:47]
	v_add_f32_e32 v8, 0, v11
	v_exp_f32_e32 v8, v8
	v_exp_f32_e32 v1, v1
	v_exp_f32_e32 v2, v2
	v_exp_f32_e32 v3, v3
	v_cndmask_b32_e64 v49, 0, v8, s[44:45]
	v_add_f32_e32 v8, 0, v12
	v_exp_f32_e32 v8, v8
	v_exp_f32_e32 v4, v4
	v_exp_f32_e32 v5, v5
	v_exp_f32_e32 v6, v6
	v_cndmask_b32_e64 v52, 0, v8, s[42:43]
	v_add_f32_e32 v8, 0, v13
	v_exp_f32_e32 v8, v8
	v_exp_f32_e32 v7, v7
	v_cndmask_b32_e64 v0, 0, v0, s[66:67]
	v_cndmask_b32_e64 v1, 0, v1, s[64:65]
	v_cndmask_b32_e64 v53, 0, v8, s[40:41]
	v_add_f32_e32 v8, 0, v14
	v_exp_f32_e32 v8, v8
	v_cndmask_b32_e64 v2, 0, v2, s[62:63]
	v_cndmask_b32_e64 v3, 0, v3, s[60:61]
	v_cndmask_b32_e64 v4, 0, v4, s[58:59]
	v_cndmask_b32_e64 v54, 0, v8, s[38:39]
	v_add_f32_e32 v8, 0, v15
	v_exp_f32_e32 v8, v8
	v_cndmask_b32_e64 v5, 0, v5, s[56:57]
	v_cndmask_b32_e64 v6, 0, v6, s[54:55]
	v_cndmask_b32_e64 v7, 0, v7, s[52:53]
	v_cvt_pk_bf16_f32 v24, v0, v1
	v_cvt_pk_bf16_f32 v25, v2, v3
	v_cvt_pk_bf16_f32 v26, v4, v5
	v_cvt_pk_bf16_f32 v27, v6, v7
	v_cndmask_b32_e32 v55, 0, v8, vcc
	v_cvt_pk_bf16_f32 v50, v42, v43
	s_waitcnt vmcnt(3)
	v_mfma_f32_32x32x16_bf16 v[0:15], v[20:23], v[24:27], 0
	v_cvt_pk_bf16_f32 v51, v45, v49
	v_cvt_pk_bf16_f32 v52, v52, v53
	v_cvt_pk_bf16_f32 v53, v54, v55
	s_movk_i32 s40, 0x1ff
	s_waitcnt vmcnt(2)
	v_mfma_f32_32x32x16_bf16 v[16:31], v[16:19], v[24:27], 0
	s_waitcnt vmcnt(1)
	v_mfma_f32_32x32x16_bf16 v[0:15], v[36:39], v[50:53], v[0:15]
	s_waitcnt vmcnt(0)
	v_mfma_f32_32x32x16_bf16 v[16:31], v[32:35], v[50:53], v[16:31]
	s_waitcnt lgkmcnt(0)
	v_add_f32_e32 v32, v40, v41
	v_cmp_gt_f32_e32 vcc, s18, v32
	s_cmp_lg_u64 vcc, exec
	s_cselect_b64 s[38:39], -1, 0
	v_cmp_ne_u32_e32 vcc, s40, v48
	s_and_b64 s[38:39], vcc, s[38:39]
	s_and_saveexec_b64 s[40:41], s[38:39]
	s_cbranch_execz .LBB0_786
	s_add_i32 s38, s19, s97
	v_add_f32_e32 v115, 0, v32
	v_add_u32_e32 v32, s38, v46
	v_sub_u32_e32 v32, 0x1fe, v32
	v_mov_b32_e32 v33, v65
	v_lshrrev_b32_e32 v34, 1, v47
	v_lshlrev_b64 v[32:33], 12, v[32:33]
	v_and_b32_e32 v34, 16, v34
	v_mov_b32_e32 v35, v65
	v_or3_b32 v36, v32, v44, v34
	v_or_b32_e32 v32, v32, v64
	v_mov_b32_e32 v37, v33
	v_lshl_add_u64 v[32:33], v[32:33], 0, v[34:35]
	v_lshl_add_u64 v[110:111], s[28:29], 0, v[36:37]
	v_lshl_add_u64 v[112:113], s[74:75], 0, v[32:33]
	s_mov_b64 s[42:43], 0
	global_load_dwordx4 v[140:143], v[112:113], off offset:-2048
	global_load_dwordx4 v[144:147], v[112:113], off offset:-1024
	global_load_dwordx4 v[148:151], v[112:113], off
	global_load_dwordx4 v[152:155], v[112:113], off offset:1024
.LBB0_791:
	global_load_dwordx4 v[102:105], v[110:111], off offset:-2048
	global_load_dwordx4 v[98:101], v[110:111], off
	global_load_dwordx4 v[90:93], v[110:111], off offset:-2016
	global_load_dwordx4 v[94:97], v[110:111], off offset:32
	v_add_u32_e32 v64, -1, v108
	v_lshl_add_u64 v[110:111], v[110:111], 0, s[14:15]
	v_lshl_add_u64 v[112:113], v[112:113], 0, s[14:15]
	s_waitcnt vmcnt(7)
	v_mfma_f32_32x32x16_bf16 v[32:47], v[140:143], v[78:81], 0
	s_waitcnt vmcnt(6)
	v_mfma_f32_32x32x16_bf16 v[32:47], v[144:147], v[74:77], v[32:47]
	s_waitcnt vmcnt(5)
	v_mfma_f32_32x32x16_bf16 v[32:47], v[148:151], v[70:73], v[32:47]
	s_waitcnt vmcnt(4)
	v_mfma_f32_32x32x16_bf16 v[32:47], v[152:155], v[66:69], v[32:47]
	global_load_dwordx4 v[140:143], v[112:113], off offset:-2048
	global_load_dwordx4 v[144:147], v[112:113], off offset:-1024
	global_load_dwordx4 v[148:151], v[112:113], off
	global_load_dwordx4 v[152:155], v[112:113], off offset:1024
	s_nop 11
	v_exp_f32_e32 v50, v34
	v_exp_f32_e32 v48, v32
	v_exp_f32_e32 v49, v33
	v_cmp_lt_f32_e32 vcc, s79, v32
	v_add_f32_e32 v50, 1.0, v50
	v_log_f32_e32 v52, v50
	v_exp_f32_e32 v50, v35
	v_add_f32_e32 v48, 1.0, v48
	v_add_f32_e32 v49, 1.0, v49
	v_log_f32_e32 v48, v48
	v_add_f32_e32 v50, 1.0, v50
	v_log_f32_e32 v53, v50
	v_exp_f32_e32 v50, v36
	v_log_f32_e32 v49, v49
	v_cmp_lt_f32_e64 s[38:39], s79, v33
	v_cndmask_b32_e32 v48, v48, v32, vcc
	v_add_f32_e32 v50, 1.0, v50
	v_log_f32_e32 v54, v50
	v_exp_f32_e32 v50, v37
	v_cndmask_b32_e64 v49, v49, v33, s[38:39]
	v_sub_f32_e64 v58, -v48, v49
	v_cmp_lt_f32_e32 vcc, s79, v34
	v_add_f32_e32 v50, 1.0, v50
	v_log_f32_e32 v55, v50
	v_exp_f32_e32 v50, v38
	v_cmp_lt_f32_e64 s[38:39], s79, v35
	v_add_f32_e32 v50, 1.0, v50
	v_log_f32_e32 v56, v50
	v_exp_f32_e32 v50, v39
	s_nop 0
	v_add_f32_e32 v50, 1.0, v50
	v_log_f32_e32 v57, v50
	v_exp_f32_e32 v50, v40
	s_nop 0
	v_add_f32_e32 v50, 1.0, v50
	v_log_f32_e32 v126, v50
	v_exp_f32_e32 v50, v41
	s_nop 0
	v_add_f32_e32 v50, 1.0, v50
	v_log_f32_e32 v127, v50
	v_exp_f32_e32 v50, v42
	s_nop 0
	v_add_f32_e32 v50, 1.0, v50
	v_log_f32_e32 v128, v50
	v_exp_f32_e32 v50, v43
	s_nop 0
	v_add_f32_e32 v50, 1.0, v50
	v_log_f32_e32 v129, v50
	v_exp_f32_e32 v50, v44
	s_nop 0
	v_add_f32_e32 v50, 1.0, v50
	v_log_f32_e32 v130, v50
	v_exp_f32_e32 v50, v45
	s_nop 0
	v_add_f32_e32 v50, 1.0, v50
	v_log_f32_e32 v131, v50
	v_exp_f32_e32 v50, v46
; DI unsigned pk_bf16(float lo, float hi) { f32x2_t v = {lo, hi}; return __builtin_bit_cast(unsigned, __builtin_convertvector(v, bf16x2_t)); }
; DI float bflo(unsigned u) { return __uint_as_float(u << 16); }
; DI float bfhi(unsigned u) { return __uint_as_float(u & 0xffff0000u); }
; DI float shfl_xor_l(float v, int mask, int lane) { return __int_as_float(__builtin_amdgcn_ds_bpermute((lane ^ mask) << 2, __float_as_int(v))); }
; DI int crow(int reg, int h) { return (reg & 3) + 8 * (reg >> 2) + 4 * h; }
; #define MFMA32(a, b, c) __builtin_amdgcn_mfma_f32_32x32x16_bf16((a), (b), (c), 0, 0, 0)
; DI void attn_task(const Params& p, int hd, int qb) {
;     ...
;     for (int e = 0; e < 16; ++e) {
;       const float zz = z[e];
;       float l = -__builtin_amdgcn_logf(1.0f + __builtin_amdgcn_exp2f(zz));
;       l = (zz > 30.f) ? -zz : l;
;       if (diag && crow(e, hh) >= r) l = 0.f;
;       lf[e] = l; sum += l;
;     }
;     sum += shfl_xor_l(sum, 32, lane);
;     f32x16 ee = z;
; #pragma unroll
;     for (int s2 = 0; s2 < 2; ++s2) {
;       u32x4 hi, lo;
; #pragma unroll
;       for (int j = 0; j < 4; ++j) {
;         const float a = lf[8 * s2 + 2 * j], b = lf[8 * s2 + 2 * j + 1];
;         hi[j] = pk_bf16(a, b);
;         lo[j] = pk_bf16(a - bflo(hi[j]), b - bfhi(hi[j]));
;       }
;       ee = MFMA32(tri[s2], __builtin_bit_cast(bf16x8, hi), ee);
;       ee = MFMA32(tri[s2], __builtin_bit_cast(bf16x8, lo), ee);
;     }
;     f32x16 wv;
; #pragma unroll
;     for (int e = 0; e < 16; ++e) {
;       float x = __builtin_amdgcn_exp2f(ee[e] + carry);
;       if (diag && crow(e, hh) >= r) x = 0.f;
;       wv[e] = x;
;     }
; #pragma unroll
;     for (int s2 = 0; s2 < 2; ++s2) {
;       const bf16x8 wp = pack8(wv, s2);
;       o0 = MFMA32(vf[s2][0], wp, o0);
;       o1 = MFMA32(vf[s2][1], wp, o1);
;     }
;     carry += sum;
;     if (__all(carry < -160.f)) break;
; #pragma unroll
;     for (int ks = 0; ks < 4; ++ks) kf[ks] = kn[ks];
;   }
	s_nop 0
	v_add_f32_e32 v50, 1.0, v50
	v_log_f32_e32 v116, v50
	v_exp_f32_e32 v50, v47
	s_nop 0
	v_add_f32_e32 v50, 1.0, v50
	v_log_f32_e32 v117, v50
	v_pk_add_f32 v[50:51], v[48:49], 0 neg_lo:[1,1] neg_hi:[1,1]
	s_nop 0
	v_cvt_pk_bf16_f32 v118, v50, v51
	v_lshlrev_b32_e32 v50, 16, v118
	v_and_b32_e32 v51, 0xffff0000, v118
	v_pk_add_f32 v[48:49], v[48:49], v[50:51] neg_lo:[1,1] neg_hi:[1,1]
	s_nop 0
	v_cvt_pk_bf16_f32 v122, v48, v49
	v_cndmask_b32_e64 v49, v53, v35, s[38:39]
	v_cndmask_b32_e32 v48, v52, v34, vcc
	v_pk_add_f32 v[50:51], v[48:49], 0 neg_lo:[1,1] neg_hi:[1,1]
	v_sub_f32_e32 v52, v58, v48
	v_cvt_pk_bf16_f32 v119, v50, v51
	v_lshlrev_b32_e32 v50, 16, v119
	v_and_b32_e32 v51, 0xffff0000, v119
	v_sub_f32_e32 v52, v52, v49
	v_pk_add_f32 v[48:49], v[48:49], v[50:51] neg_lo:[1,1] neg_hi:[1,1]
	v_cmp_lt_f32_e32 vcc, s79, v36
	v_cmp_lt_f32_e64 s[38:39], s79, v37
	v_cvt_pk_bf16_f32 v123, v48, v49
	v_cndmask_b32_e32 v48, v54, v36, vcc
	v_cndmask_b32_e64 v49, v55, v37, s[38:39]
	v_pk_add_f32 v[50:51], v[48:49], 0 neg_lo:[1,1] neg_hi:[1,1]
	v_sub_f32_e32 v52, v52, v48
	v_cvt_pk_bf16_f32 v120, v50, v51
	v_lshlrev_b32_e32 v50, 16, v120
	v_and_b32_e32 v51, 0xffff0000, v120
	v_sub_f32_e32 v52, v52, v49
	v_pk_add_f32 v[48:49], v[48:49], v[50:51] neg_lo:[1,1] neg_hi:[1,1]
	v_cmp_lt_f32_e32 vcc, s79, v38
	v_cmp_lt_f32_e64 s[38:39], s79, v39
	v_cvt_pk_bf16_f32 v124, v48, v49
	v_cndmask_b32_e32 v48, v56, v38, vcc
	v_cndmask_b32_e64 v49, v57, v39, s[38:39]
	v_pk_add_f32 v[50:51], v[48:49], 0 neg_lo:[1,1] neg_hi:[1,1]
	v_sub_f32_e32 v52, v52, v48
	v_cvt_pk_bf16_f32 v121, v50, v51
	v_lshlrev_b32_e32 v50, 16, v121
	v_and_b32_e32 v51, 0xffff0000, v121
	v_sub_f32_e32 v132, v52, v49
	v_pk_add_f32 v[48:49], v[48:49], v[50:51] neg_lo:[1,1] neg_hi:[1,1]
	v_cmp_lt_f32_e32 vcc, s79, v40
	v_cmp_lt_f32_e64 s[38:39], s79, v41
	v_cvt_pk_bf16_f32 v125, v48, v49
	v_mfma_f32_32x32x16_bf16 v[48:63], v[82:85], v[118:121], v[32:47]
	s_nop 6
	v_cndmask_b32_e64 v33, v127, v41, s[38:39]
	v_cndmask_b32_e32 v32, v126, v40, vcc
	v_add_f32_e64 v34, -v32, neg(0)
	v_add_f32_e64 v35, -v33, neg(0)
	v_sub_f32_e32 v36, v132, v32
	v_sub_f32_e32 v37, v36, v33
	v_cvt_pk_bf16_f32 v36, v34, v35
	v_lshlrev_b32_e32 v34, 16, v36
	v_and_b32_e32 v35, 0xffff0000, v36
	v_cmp_lt_f32_e32 vcc, s79, v42
	v_cmp_lt_f32_e64 s[38:39], s79, v43
	v_pk_add_f32 v[32:33], v[32:33], v[34:35] neg_lo:[1,1] neg_hi:[1,1]
	v_cndmask_b32_e32 v34, v128, v42, vcc
	v_cndmask_b32_e64 v35, v129, v43, s[38:39]
	v_pk_add_f32 v[38:39], v[34:35], 0 neg_lo:[1,1] neg_hi:[1,1]
	v_cvt_pk_bf16_f32 v32, v32, v33
	v_sub_f32_e32 v33, v37, v34
	v_cvt_pk_bf16_f32 v37, v38, v39
	v_lshlrev_b32_e32 v38, 16, v37
	v_and_b32_e32 v39, 0xffff0000, v37
	v_mfma_f32_32x32x16_bf16 v[48:63], v[82:85], v[122:125], v[48:63]
	v_sub_f32_e32 v40, v33, v35
	v_add_f32_e64 v34, -v34, -v38
	v_add_f32_e64 v35, -v35, -v39
	v_cmp_lt_f32_e32 vcc, s79, v44
	v_cmp_lt_f32_e64 s[38:39], s79, v45
	v_cvt_pk_bf16_f32 v33, v34, v35
	v_cndmask_b32_e32 v34, v130, v44, vcc
	v_cndmask_b32_e64 v35, v131, v45, s[38:39]
	v_pk_add_f32 v[38:39], v[34:35], 0 neg_lo:[1,1] neg_hi:[1,1]
	v_sub_f32_e32 v40, v40, v34
	v_cvt_pk_bf16_f32 v38, v38, v39
	v_sub_f32_e32 v44, v40, v35
	v_lshlrev_b32_e32 v40, 16, v38
	v_and_b32_e32 v41, 0xffff0000, v38
	v_cmp_lt_f32_e32 vcc, s79, v46
	v_cmp_lt_f32_e64 s[38:39], s79, v47
	v_pk_add_f32 v[34:35], v[34:35], v[40:41] neg_lo:[1,1] neg_hi:[1,1]
	v_cndmask_b32_e32 v40, v116, v46, vcc
	v_cndmask_b32_e64 v41, v117, v47, s[38:39]
	v_pk_add_f32 v[42:43], v[40:41], 0 neg_lo:[1,1] neg_hi:[1,1]
	v_cvt_pk_bf16_f32 v34, v34, v35
	v_cvt_pk_bf16_f32 v39, v42, v43
	v_sub_f32_e32 v35, v44, v40
	v_lshlrev_b32_e32 v42, 16, v39
	v_mfma_f32_32x32x16_bf16 v[48:63], v[86:89], v[36:39], v[48:63]
	v_and_b32_e32 v43, 0xffff0000, v39
	v_sub_f32_e32 v44, v35, v41
	v_add_f32_e64 v40, -v40, -v42
	v_add_f32_e64 v41, -v41, -v43
	ds_bpermute_b32 v45, v109, v44
	v_cvt_pk_bf16_f32 v35, v40, v41
	s_nop 1
	v_mfma_f32_32x32x16_bf16 v[48:63], v[86:89], v[32:35], v[48:63]
	s_nop 11
	v_add_f32_e32 v32, v115, v48
	v_add_f32_e32 v33, v115, v49
	v_add_f32_e32 v34, v115, v50
	v_add_f32_e32 v35, v115, v51
	v_add_f32_e32 v36, v115, v52
	v_add_f32_e32 v37, v115, v53
	v_add_f32_e32 v38, v115, v54
	v_add_f32_e32 v39, v115, v55
	v_exp_f32_e32 v32, v32
	v_exp_f32_e32 v33, v33
	v_exp_f32_e32 v34, v34
	v_exp_f32_e32 v35, v35
	v_exp_f32_e32 v36, v36
	v_exp_f32_e32 v37, v37
	v_exp_f32_e32 v38, v38
	v_exp_f32_e32 v39, v39
	v_cvt_pk_bf16_f32 v32, v32, v33
	v_cvt_pk_bf16_f32 v33, v34, v35
	v_cvt_pk_bf16_f32 v34, v36, v37
	v_cvt_pk_bf16_f32 v35, v38, v39
	v_add_f32_e32 v40, v115, v56
	v_add_f32_e32 v41, v115, v57
	s_waitcnt vmcnt(7)
	v_mfma_f32_32x32x16_bf16 v[0:15], v[102:105], v[32:35], v[0:15]
	v_add_f32_e32 v42, v115, v58
	v_add_f32_e32 v43, v115, v59
	v_add_f32_e32 v46, v115, v60
	v_add_f32_e32 v47, v115, v61
	v_add_f32_e32 v48, v115, v62
	v_add_f32_e32 v49, v115, v63
	v_exp_f32_e32 v40, v40
	s_waitcnt vmcnt(6)
	v_mfma_f32_32x32x16_bf16 v[16:31], v[98:101], v[32:35], v[16:31]
	v_exp_f32_e32 v41, v41
	v_exp_f32_e32 v42, v42
	v_exp_f32_e32 v43, v43
	v_exp_f32_e32 v46, v46
	v_exp_f32_e32 v47, v47
	v_exp_f32_e32 v48, v48
	v_exp_f32_e32 v49, v49
	v_cvt_pk_bf16_f32 v32, v40, v41
	v_cvt_pk_bf16_f32 v33, v42, v43
	v_cvt_pk_bf16_f32 v34, v46, v47
	v_cvt_pk_bf16_f32 v35, v48, v49
	s_waitcnt vmcnt(5)
	s_nop 0
	v_mfma_f32_32x32x16_bf16 v[0:15], v[90:93], v[32:35], v[0:15]
	s_waitcnt vmcnt(4)
	v_mfma_f32_32x32x16_bf16 v[16:31], v[94:97], v[32:35], v[16:31]
	s_waitcnt lgkmcnt(0)
	v_add_f32_e32 v32, v44, v45
	v_add_f32_e32 v115, v115, v32
	v_cmp_gt_f32_e32 vcc, s18, v115
	s_cmp_eq_u64 vcc, exec
	s_cselect_b64 s[38:39], -1, 0
	v_cmp_gt_u32_e32 vcc, 2, v108
	s_or_b64 s[38:39], s[38:39], vcc
	s_and_b64 s[38:39], exec, s[38:39]
	s_or_b64 s[42:43], s[38:39], s[42:43]
	v_mov_b32_e32 v108, v64
	s_andn2_b64 exec, exec, s[42:43]
	s_cbranch_execnz .LBB0_791
	s_or_b64 exec, exec, s[42:43]
	s_branch .LBB0_786
